# conv+SiLU epilogue of FFN-up processed 8 rows per iteration (ILP), on top of pipelined k-loop
# speedup vs baseline: 1.0535x; 1.0216x over previous
.LBB0_683:
	s_or_b64 exec, exec, s[4:5]
	v_pk_mul_f32 v[2:3], v[2:3], v[66:67] op_sel_hi:[1,0]
	ds_write2_b32 v155, v2, v3 offset0:32 offset1:33
	v_pk_mul_f32 v[2:3], v[4:5], v[66:67] op_sel_hi:[1,0]
	ds_write2_b32 v155, v2, v3 offset0:34 offset1:35
	v_pk_mul_f32 v[2:3], v[6:7], v[66:67] op_sel_hi:[1,0]
	ds_write2_b32 v155, v2, v3 offset0:40 offset1:41
	v_pk_mul_f32 v[2:3], v[8:9], v[66:67] op_sel_hi:[1,0]
	ds_write2_b32 v155, v2, v3 offset0:42 offset1:43
	v_pk_mul_f32 v[2:3], v[10:11], v[66:67] op_sel_hi:[1,0]
	ds_write2_b32 v155, v2, v3 offset0:48 offset1:49
	v_pk_mul_f32 v[2:3], v[12:13], v[66:67] op_sel_hi:[1,0]
	s_load_dwordx8 s[4:11], s[0:1], 0xc0
	ds_write2_b32 v155, v2, v3 offset0:50 offset1:51
	v_pk_mul_f32 v[2:3], v[14:15], v[66:67] op_sel_hi:[1,0]
	ds_write2_b32 v155, v2, v3 offset0:56 offset1:57
	v_pk_mul_f32 v[2:3], v[16:17], v[66:67] op_sel_hi:[1,0]
	ds_write2_b32 v155, v2, v3 offset0:58 offset1:59
	v_lshl_or_b32 v2, s14, 6, v114
	v_ashrrev_i32_e32 v3, 31, v2
	v_lshlrev_b64 v[8:9], 2, v[2:3]
	s_waitcnt lgkmcnt(0)
	s_mov_b64 s[4:5], s[8:9]
	v_lshl_add_u64 v[10:11], s[4:5], 0, v[8:9]
	v_pk_mul_f32 v[18:19], v[18:19], v[66:67] op_sel_hi:[1,0]
	v_add_co_u32_e32 v4, vcc, s24, v10
	ds_write2_b32 v155, v18, v19 offset1:1
	v_pk_mul_f32 v[18:19], v[20:21], v[66:67] op_sel_hi:[1,0]
	v_addc_co_u32_e32 v5, vcc, 0, v11, vcc
	ds_write2_b32 v155, v18, v19 offset0:2 offset1:3
	v_pk_mul_f32 v[18:19], v[22:23], v[66:67] op_sel_hi:[1,0]
	v_add_co_u32_e32 v6, vcc, s28, v10
	ds_write2_b32 v155, v18, v19 offset0:8 offset1:9
	v_pk_mul_f32 v[18:19], v[24:25], v[66:67] op_sel_hi:[1,0]
	v_addc_co_u32_e32 v7, vcc, 0, v11, vcc
	ds_write2_b32 v155, v18, v19 offset0:10 offset1:11
	v_pk_mul_f32 v[18:19], v[26:27], v[66:67] op_sel_hi:[1,0]
	v_add_co_u32_e32 v14, vcc, s22, v10
	ds_write2_b32 v155, v18, v19 offset0:16 offset1:17
	v_pk_mul_f32 v[18:19], v[28:29], v[66:67] op_sel_hi:[1,0]
	v_addc_co_u32_e32 v15, vcc, 0, v11, vcc
	ds_write2_b32 v155, v18, v19 offset0:18 offset1:19
	v_pk_mul_f32 v[18:19], v[30:31], v[66:67] op_sel_hi:[1,0]
	v_add_co_u32_e32 v16, vcc, s29, v10
	ds_write2_b32 v155, v18, v19 offset0:24 offset1:25
	v_pk_mul_f32 v[18:19], v[32:33], v[66:67] op_sel_hi:[1,0]
	v_addc_co_u32_e32 v17, vcc, 0, v11, vcc
	ds_write2_b32 v155, v18, v19 offset0:26 offset1:27
	s_waitcnt lgkmcnt(0)
	s_barrier
	s_mov_b64 s[6:7], s[10:11]
	global_load_dword v3, v[10:11], off
	s_nop 0
	global_load_dword v5, v[4:5], off offset:2048
	s_nop 0
	global_load_dword v7, v[6:7], off
	v_add_co_u32_e32 v10, vcc, s33, v10
	v_lshl_add_u64 v[12:13], s[6:7], 0, v[8:9]
	s_nop 0
	v_addc_co_u32_e32 v11, vcc, 0, v11, vcc
	global_load_dword v9, v[12:13], off
	global_load_dword v2, v[14:15], off offset:3072
	global_load_dword v4, v[16:17], off offset:1024
	global_load_dword v6, v[10:11], off offset:3072
	v_add_co_u32_e32 v10, vcc, s22, v12
	s_mul_i32 s4, s51, 0x7e
	s_nop 0
	v_addc_co_u32_e32 v11, vcc, 0, v13, vcc
	global_load_dword v8, v[10:11], off offset:3072
	ds_read_b32 v15, v159
	ds_read_b32 v10, v160
	ds_read_b32 v14, v161
	ds_read_b32 v11, v162
	s_add_i32 s4, s21, s4
	s_mulk_i32 s52, 0x7c
	s_sub_i32 s10, s4, s52
	v_add_lshl_u32 v16, v167, s53, 6
	s_mov_b64 s[4:5], 0
	v_mov_b32_e32 v17, v158
	v_mov_b32_e32 v18, v156
	s_waitcnt vmcnt(0)
	s_add_i32 s63, s10, -2
	s_sub_i32 s64, s22, s50
	v_min_i32_e32 v40, s64, v157
	v_add_u32_e32 v40, s63, v40
	v_lshlrev_b32_e32 v41, 1, v114
	s_mov_b32 s62, 4
.Lcv5_loop:
	ds_read_b32 v188, v17
	ds_read_b32 v196, v17 offset:256
	ds_read_b32 v189, v17 offset:516
	ds_read_b32 v197, v17 offset:772
	ds_read_b32 v190, v17 offset:1032
	ds_read_b32 v198, v17 offset:1288
	ds_read_b32 v191, v17 offset:1548
	ds_read_b32 v199, v17 offset:1804
	ds_read_b32 v192, v17 offset:2064
	ds_read_b32 v200, v17 offset:2320
	ds_read_b32 v193, v17 offset:2580
	ds_read_b32 v201, v17 offset:2836
	ds_read_b32 v194, v17 offset:3096
	ds_read_b32 v202, v17 offset:3352
	ds_read_b32 v195, v17 offset:3612
	ds_read_b32 v203, v17 offset:3868
	v_add3_u32 v32, s63, v18, 0
	v_add3_u32 v33, s63, v18, 1
	v_add3_u32 v34, s63, v18, 2
	v_add3_u32 v35, s63, v18, 3
	v_add3_u32 v36, s63, v18, 4
	v_add3_u32 v37, s63, v18, 5
	v_add3_u32 v38, s63, v18, 6
	v_add3_u32 v39, s63, v18, 7
	v_ashrrev_i32_e32 v220, 7, v32
	v_ashrrev_i32_e32 v221, 7, v33
	v_ashrrev_i32_e32 v222, 7, v34
	v_ashrrev_i32_e32 v223, 7, v35
	v_ashrrev_i32_e32 v224, 7, v36
	v_ashrrev_i32_e32 v225, 7, v37
	v_ashrrev_i32_e32 v226, 7, v38
	v_ashrrev_i32_e32 v227, 7, v39
	v_mad_u32_u24 v220, v220, 44, s14
	v_mad_u32_u24 v221, v221, 44, s14
	v_mad_u32_u24 v222, v222, 44, s14
	v_mad_u32_u24 v223, v223, 44, s14
	v_mad_u32_u24 v224, v224, 44, s14
	v_mad_u32_u24 v225, v225, 44, s14
	v_mad_u32_u24 v226, v226, 44, s14
	v_mad_u32_u24 v227, v227, 44, s14
	v_and_b32_e32 v24, 0x7f, v32
	v_and_b32_e32 v25, 0x7f, v33
	v_and_b32_e32 v26, 0x7f, v34
	v_and_b32_e32 v27, 0x7f, v35
	v_and_b32_e32 v28, 0x7f, v36
	v_and_b32_e32 v29, 0x7f, v37
	v_and_b32_e32 v30, 0x7f, v38
	v_and_b32_e32 v31, 0x7f, v39
	v_lshlrev_b32_e32 v24, 7, v24
	v_lshlrev_b32_e32 v25, 7, v25
	v_lshlrev_b32_e32 v26, 7, v26
	v_lshlrev_b32_e32 v27, 7, v27
	v_lshlrev_b32_e32 v28, 7, v28
	v_lshlrev_b32_e32 v29, 7, v29
	v_lshlrev_b32_e32 v30, 7, v30
	v_lshlrev_b32_e32 v31, 7, v31
	v_lshl_or_b32 v24, v220, 14, v24
	v_lshl_or_b32 v25, v221, 14, v25
	v_lshl_or_b32 v26, v222, 14, v26
	v_lshl_or_b32 v27, v223, 14, v27
	v_lshl_or_b32 v28, v224, 14, v28
	v_lshl_or_b32 v29, v225, 14, v29
	v_lshl_or_b32 v30, v226, 14, v30
	v_lshl_or_b32 v31, v227, 14, v31
	v_add_u32_e32 v24, v24, v41
	v_add_u32_e32 v25, v25, v41
	v_add_u32_e32 v26, v26, v41
	v_add_u32_e32 v27, v27, v41
	v_add_u32_e32 v28, v28, v41
	v_add_u32_e32 v29, v29, v41
	v_add_u32_e32 v30, v30, v41
	v_add_u32_e32 v31, v31, v41
	s_waitcnt lgkmcnt(0)
	v_fma_f32 v204, v3, v15, v9
	v_fma_f32 v212, v2, v14, v8
	v_fma_f32 v205, v3, v10, v9
	v_fma_f32 v213, v2, v11, v8
	v_fma_f32 v206, v3, v188, v9
	v_fma_f32 v214, v2, v196, v8
	v_fma_f32 v207, v3, v189, v9
	v_fma_f32 v215, v2, v197, v8
	v_fma_f32 v208, v3, v190, v9
	v_fma_f32 v216, v2, v198, v8
	v_fma_f32 v209, v3, v191, v9
	v_fma_f32 v217, v2, v199, v8
	v_fma_f32 v210, v3, v192, v9
	v_fma_f32 v218, v2, v200, v8
	v_fma_f32 v211, v3, v193, v9
	v_fma_f32 v219, v2, v201, v8
	v_fma_f32 v204, v5, v10, v204
	v_fma_f32 v212, v4, v11, v212
	v_fma_f32 v205, v5, v188, v205
	v_fma_f32 v213, v4, v196, v213
	v_fma_f32 v206, v5, v189, v206
	v_fma_f32 v214, v4, v197, v214
	v_fma_f32 v207, v5, v190, v207
	v_fma_f32 v215, v4, v198, v215
	v_fma_f32 v208, v5, v191, v208
	v_fma_f32 v216, v4, v199, v216
	v_fma_f32 v209, v5, v192, v209
	v_fma_f32 v217, v4, v200, v217
	v_fma_f32 v210, v5, v193, v210
	v_fma_f32 v218, v4, v201, v218
	v_fma_f32 v211, v5, v194, v211
	v_fma_f32 v219, v4, v202, v219
	v_fma_f32 v204, v7, v188, v204
	v_fma_f32 v212, v6, v196, v212
	v_fma_f32 v205, v7, v189, v205
	v_fma_f32 v213, v6, v197, v213
	v_fma_f32 v206, v7, v190, v206
	v_fma_f32 v214, v6, v198, v214
	v_fma_f32 v207, v7, v191, v207
	v_fma_f32 v215, v6, v199, v215
	v_fma_f32 v208, v7, v192, v208
	v_fma_f32 v216, v6, v200, v216
	v_fma_f32 v209, v7, v193, v209
	v_fma_f32 v217, v6, v201, v217
	v_fma_f32 v210, v7, v194, v210
	v_fma_f32 v218, v6, v202, v218
	v_fma_f32 v211, v7, v195, v211
	v_fma_f32 v219, v6, v203, v219
	v_mul_f32_e32 v220, 0xbfb8aa3b, v204
	v_mul_f32_e32 v221, 0xbfb8aa3b, v205
	v_mul_f32_e32 v222, 0xbfb8aa3b, v206
	v_mul_f32_e32 v223, 0xbfb8aa3b, v207
	v_mul_f32_e32 v224, 0xbfb8aa3b, v208
	v_mul_f32_e32 v225, 0xbfb8aa3b, v209
	v_mul_f32_e32 v226, 0xbfb8aa3b, v210
	v_mul_f32_e32 v227, 0xbfb8aa3b, v211
	v_exp_f32_e32 v220, v220
	v_exp_f32_e32 v221, v221
	v_exp_f32_e32 v222, v222
	v_exp_f32_e32 v223, v223
	v_exp_f32_e32 v224, v224
	v_exp_f32_e32 v225, v225
	v_exp_f32_e32 v226, v226
	v_exp_f32_e32 v227, v227
	v_add_f32_e32 v220, 1.0, v220
	v_add_f32_e32 v221, 1.0, v221
	v_add_f32_e32 v222, 1.0, v222
	v_add_f32_e32 v223, 1.0, v223
	v_add_f32_e32 v224, 1.0, v224
	v_add_f32_e32 v225, 1.0, v225
	v_add_f32_e32 v226, 1.0, v226
	v_add_f32_e32 v227, 1.0, v227
	v_rcp_f32_e32 v220, v220
	v_rcp_f32_e32 v221, v221
	v_rcp_f32_e32 v222, v222
	v_rcp_f32_e32 v223, v223
	v_rcp_f32_e32 v224, v224
	v_rcp_f32_e32 v225, v225
	v_rcp_f32_e32 v226, v226
	v_rcp_f32_e32 v227, v227
	v_mov_b32_e32 v15, v194
	v_mov_b32_e32 v10, v195
	v_mov_b32_e32 v14, v202
	v_mov_b32_e32 v11, v203
	v_mul_f32_e32 v204, v204, v220
	v_mul_f32_e32 v205, v205, v221
	v_mul_f32_e32 v206, v206, v222
	v_mul_f32_e32 v207, v207, v223
	v_mul_f32_e32 v208, v208, v224
	v_mul_f32_e32 v209, v209, v225
	v_mul_f32_e32 v210, v210, v226
	v_mul_f32_e32 v211, v211, v227
	v_mul_f32_e32 v212, v212, v204
	v_mul_f32_e32 v213, v213, v205
	v_mul_f32_e32 v214, v214, v206
	v_mul_f32_e32 v215, v215, v207
	v_mul_f32_e32 v216, v216, v208
	v_mul_f32_e32 v217, v217, v209
	v_mul_f32_e32 v218, v218, v210
	v_mul_f32_e32 v219, v219, v211
	v_cvt_pk_bf16_f32 v212, v212, v212
	v_cvt_pk_bf16_f32 v213, v213, v213
	v_cvt_pk_bf16_f32 v214, v214, v214
	v_cvt_pk_bf16_f32 v215, v215, v215
	v_cvt_pk_bf16_f32 v216, v216, v216
	v_cvt_pk_bf16_f32 v217, v217, v217
	v_cvt_pk_bf16_f32 v218, v218, v218
	v_cvt_pk_bf16_f32 v219, v219, v219
	v_cmp_lt_i32_e32 vcc, v32, v40
	s_and_b64 exec, exec, vcc
	global_store_short v24, v212, s[42:43]
	v_cmp_lt_i32_e32 vcc, v33, v40
	s_and_b64 exec, exec, vcc
	global_store_short v25, v213, s[42:43]
	v_cmp_lt_i32_e32 vcc, v34, v40
	s_and_b64 exec, exec, vcc
	global_store_short v26, v214, s[42:43]
	v_cmp_lt_i32_e32 vcc, v35, v40
	s_and_b64 exec, exec, vcc
	global_store_short v27, v215, s[42:43]
	v_cmp_lt_i32_e32 vcc, v36, v40
	s_and_b64 exec, exec, vcc
	global_store_short v28, v216, s[42:43]
	v_cmp_lt_i32_e32 vcc, v37, v40
	s_and_b64 exec, exec, vcc
	global_store_short v29, v217, s[42:43]
	v_cmp_lt_i32_e32 vcc, v38, v40
	s_and_b64 exec, exec, vcc
	global_store_short v30, v218, s[42:43]
	v_cmp_lt_i32_e32 vcc, v39, v40
	s_and_b64 exec, exec, vcc
	global_store_short v31, v219, s[42:43]
	s_mov_b64 exec, -1
	v_add_u32_e32 v17, 0x1020, v17
	v_add_u32_e32 v18, 8, v18
	s_sub_u32 s62, s62, 1
	s_cmp_lg_u32 s62, 0
	s_cbranch_scc1 .Lcv5_loop
	s_branch .LBB0_646

.LBB0_2400:
	s_or_b64 exec, exec, s[4:5]
	v_pk_mul_f32 v[2:3], v[2:3], v[66:67] op_sel_hi:[1,0]
	ds_write2_b32 v155, v2, v3 offset0:32 offset1:33
	v_pk_mul_f32 v[2:3], v[4:5], v[66:67] op_sel_hi:[1,0]
	ds_write2_b32 v155, v2, v3 offset0:34 offset1:35
	v_pk_mul_f32 v[2:3], v[6:7], v[66:67] op_sel_hi:[1,0]
	ds_write2_b32 v155, v2, v3 offset0:40 offset1:41
	v_pk_mul_f32 v[2:3], v[8:9], v[66:67] op_sel_hi:[1,0]
	ds_write2_b32 v155, v2, v3 offset0:42 offset1:43
	v_pk_mul_f32 v[2:3], v[10:11], v[66:67] op_sel_hi:[1,0]
	ds_write2_b32 v155, v2, v3 offset0:48 offset1:49
	v_pk_mul_f32 v[2:3], v[12:13], v[66:67] op_sel_hi:[1,0]
	ds_write2_b32 v155, v2, v3 offset0:50 offset1:51
	v_pk_mul_f32 v[2:3], v[14:15], v[66:67] op_sel_hi:[1,0]
	ds_write2_b32 v155, v2, v3 offset0:56 offset1:57
	v_pk_mul_f32 v[2:3], v[16:17], v[66:67] op_sel_hi:[1,0]
	v_pk_mul_f32 v[18:19], v[18:19], v[66:67] op_sel_hi:[1,0]
	ds_write2_b32 v155, v2, v3 offset0:58 offset1:59
	v_lshl_or_b32 v2, s18, 6, v114
	ds_write2_b32 v155, v18, v19 offset1:1
	v_pk_mul_f32 v[18:19], v[20:21], v[66:67] op_sel_hi:[1,0]
	v_ashrrev_i32_e32 v3, 31, v2
	ds_write2_b32 v155, v18, v19 offset0:2 offset1:3
	v_pk_mul_f32 v[18:19], v[22:23], v[66:67] op_sel_hi:[1,0]
	v_lshlrev_b64 v[8:9], 2, v[2:3]
	ds_write2_b32 v155, v18, v19 offset0:8 offset1:9
	v_pk_mul_f32 v[18:19], v[24:25], v[66:67] op_sel_hi:[1,0]
	v_lshl_add_u64 v[10:11], s[14:15], 0, v[8:9]
	ds_write2_b32 v155, v18, v19 offset0:10 offset1:11
	v_pk_mul_f32 v[18:19], v[26:27], v[66:67] op_sel_hi:[1,0]
	v_add_co_u32_e32 v12, vcc, s28, v10
	ds_write2_b32 v155, v18, v19 offset0:16 offset1:17
	v_pk_mul_f32 v[18:19], v[28:29], v[66:67] op_sel_hi:[1,0]
	v_addc_co_u32_e32 v13, vcc, 0, v11, vcc
	ds_write2_b32 v155, v18, v19 offset0:18 offset1:19
	v_pk_mul_f32 v[18:19], v[30:31], v[66:67] op_sel_hi:[1,0]
	v_add_co_u32_e32 v14, vcc, s30, v10
	ds_write2_b32 v155, v18, v19 offset0:24 offset1:25
	v_pk_mul_f32 v[18:19], v[32:33], v[66:67] op_sel_hi:[1,0]
	v_addc_co_u32_e32 v15, vcc, 0, v11, vcc
	ds_write2_b32 v155, v18, v19 offset0:26 offset1:27
	s_waitcnt lgkmcnt(0)
	s_barrier
	global_load_dword v3, v[10:11], off
	global_load_dword v5, v[12:13], off offset:2048
	global_load_dword v7, v[14:15], off
	v_add_co_u32_e32 v14, vcc, s26, v10
	v_lshl_add_u64 v[12:13], s[16:17], 0, v[8:9]
	s_nop 0
	v_addc_co_u32_e32 v15, vcc, 0, v11, vcc
	v_add_co_u32_e32 v16, vcc, s31, v10
	global_load_dword v9, v[12:13], off
	s_nop 0
	v_addc_co_u32_e32 v17, vcc, 0, v11, vcc
	v_add_co_u32_e32 v10, vcc, s33, v10
	s_mul_i32 s4, s37, 0x7e
	s_nop 0
	v_addc_co_u32_e32 v11, vcc, 0, v11, vcc
	global_load_dword v2, v[14:15], off offset:3072
	global_load_dword v4, v[16:17], off offset:1024
	global_load_dword v6, v[10:11], off offset:3072
	v_add_co_u32_e32 v10, vcc, s26, v12
	s_add_i32 s4, s25, s4
	s_nop 0
	v_addc_co_u32_e32 v11, vcc, 0, v13, vcc
	global_load_dword v8, v[10:11], off offset:3072
	ds_read_b32 v15, v159
	ds_read_b32 v10, v160
	ds_read_b32 v14, v161
	ds_read_b32 v11, v162
	s_mulk_i32 s38, 0x7c
	s_sub_i32 s10, s4, s38
	v_add_lshl_u32 v16, v167, s39, 6
	s_mov_b64 s[4:5], 0
	v_mov_b32_e32 v17, v158
	v_mov_b32_e32 v18, v156
	s_waitcnt vmcnt(0)
	s_add_i32 s63, s10, -2
	s_sub_i32 s64, s26, s36
	v_min_i32_e32 v40, s64, v157
	v_add_u32_e32 v40, s63, v40
	v_lshlrev_b32_e32 v41, 1, v114
	s_mov_b32 s62, 4
.Lcv12_loop:
	ds_read_b32 v188, v17
	ds_read_b32 v196, v17 offset:256
	ds_read_b32 v189, v17 offset:516
	ds_read_b32 v197, v17 offset:772
	ds_read_b32 v190, v17 offset:1032
	ds_read_b32 v198, v17 offset:1288
	ds_read_b32 v191, v17 offset:1548
	ds_read_b32 v199, v17 offset:1804
	ds_read_b32 v192, v17 offset:2064
	ds_read_b32 v200, v17 offset:2320
	ds_read_b32 v193, v17 offset:2580
	ds_read_b32 v201, v17 offset:2836
	ds_read_b32 v194, v17 offset:3096
	ds_read_b32 v202, v17 offset:3352
	ds_read_b32 v195, v17 offset:3612
	ds_read_b32 v203, v17 offset:3868
	v_add3_u32 v32, s63, v18, 0
	v_add3_u32 v33, s63, v18, 1
	v_add3_u32 v34, s63, v18, 2
	v_add3_u32 v35, s63, v18, 3
	v_add3_u32 v36, s63, v18, 4
	v_add3_u32 v37, s63, v18, 5
	v_add3_u32 v38, s63, v18, 6
	v_add3_u32 v39, s63, v18, 7
	v_ashrrev_i32_e32 v220, 7, v32
	v_ashrrev_i32_e32 v221, 7, v33
	v_ashrrev_i32_e32 v222, 7, v34
	v_ashrrev_i32_e32 v223, 7, v35
	v_ashrrev_i32_e32 v224, 7, v36
	v_ashrrev_i32_e32 v225, 7, v37
	v_ashrrev_i32_e32 v226, 7, v38
	v_ashrrev_i32_e32 v227, 7, v39
	v_mad_u32_u24 v220, v220, 44, s18
	v_mad_u32_u24 v221, v221, 44, s18
	v_mad_u32_u24 v222, v222, 44, s18
	v_mad_u32_u24 v223, v223, 44, s18
	v_mad_u32_u24 v224, v224, 44, s18
	v_mad_u32_u24 v225, v225, 44, s18
	v_mad_u32_u24 v226, v226, 44, s18
	v_mad_u32_u24 v227, v227, 44, s18
	v_and_b32_e32 v24, 0x7f, v32
	v_and_b32_e32 v25, 0x7f, v33
	v_and_b32_e32 v26, 0x7f, v34
	v_and_b32_e32 v27, 0x7f, v35
	v_and_b32_e32 v28, 0x7f, v36
	v_and_b32_e32 v29, 0x7f, v37
	v_and_b32_e32 v30, 0x7f, v38
	v_and_b32_e32 v31, 0x7f, v39
	v_lshlrev_b32_e32 v24, 7, v24
	v_lshlrev_b32_e32 v25, 7, v25
	v_lshlrev_b32_e32 v26, 7, v26
	v_lshlrev_b32_e32 v27, 7, v27
	v_lshlrev_b32_e32 v28, 7, v28
	v_lshlrev_b32_e32 v29, 7, v29
	v_lshlrev_b32_e32 v30, 7, v30
	v_lshlrev_b32_e32 v31, 7, v31
	v_lshl_or_b32 v24, v220, 14, v24
	v_lshl_or_b32 v25, v221, 14, v25
	v_lshl_or_b32 v26, v222, 14, v26
	v_lshl_or_b32 v27, v223, 14, v27
	v_lshl_or_b32 v28, v224, 14, v28
	v_lshl_or_b32 v29, v225, 14, v29
	v_lshl_or_b32 v30, v226, 14, v30
	v_lshl_or_b32 v31, v227, 14, v31
	v_add_u32_e32 v24, v24, v41
	v_add_u32_e32 v25, v25, v41
	v_add_u32_e32 v26, v26, v41
	v_add_u32_e32 v27, v27, v41
	v_add_u32_e32 v28, v28, v41
	v_add_u32_e32 v29, v29, v41
	v_add_u32_e32 v30, v30, v41
	v_add_u32_e32 v31, v31, v41
	s_waitcnt lgkmcnt(0)
	v_fma_f32 v204, v3, v15, v9
	v_fma_f32 v212, v2, v14, v8
	v_fma_f32 v205, v3, v10, v9
	v_fma_f32 v213, v2, v11, v8
	v_fma_f32 v206, v3, v188, v9
	v_fma_f32 v214, v2, v196, v8
	v_fma_f32 v207, v3, v189, v9
	v_fma_f32 v215, v2, v197, v8
	v_fma_f32 v208, v3, v190, v9
	v_fma_f32 v216, v2, v198, v8
	v_fma_f32 v209, v3, v191, v9
	v_fma_f32 v217, v2, v199, v8
	v_fma_f32 v210, v3, v192, v9
	v_fma_f32 v218, v2, v200, v8
	v_fma_f32 v211, v3, v193, v9
	v_fma_f32 v219, v2, v201, v8
	v_fma_f32 v204, v5, v10, v204
	v_fma_f32 v212, v4, v11, v212
	v_fma_f32 v205, v5, v188, v205
	v_fma_f32 v213, v4, v196, v213
	v_fma_f32 v206, v5, v189, v206
	v_fma_f32 v214, v4, v197, v214
	v_fma_f32 v207, v5, v190, v207
	v_fma_f32 v215, v4, v198, v215
	v_fma_f32 v208, v5, v191, v208
	v_fma_f32 v216, v4, v199, v216
	v_fma_f32 v209, v5, v192, v209
	v_fma_f32 v217, v4, v200, v217
	v_fma_f32 v210, v5, v193, v210
	v_fma_f32 v218, v4, v201, v218
	v_fma_f32 v211, v5, v194, v211
	v_fma_f32 v219, v4, v202, v219
	v_fma_f32 v204, v7, v188, v204
	v_fma_f32 v212, v6, v196, v212
	v_fma_f32 v205, v7, v189, v205
	v_fma_f32 v213, v6, v197, v213
	v_fma_f32 v206, v7, v190, v206
	v_fma_f32 v214, v6, v198, v214
	v_fma_f32 v207, v7, v191, v207
	v_fma_f32 v215, v6, v199, v215
	v_fma_f32 v208, v7, v192, v208
	v_fma_f32 v216, v6, v200, v216
	v_fma_f32 v209, v7, v193, v209
	v_fma_f32 v217, v6, v201, v217
	v_fma_f32 v210, v7, v194, v210
	v_fma_f32 v218, v6, v202, v218
	v_fma_f32 v211, v7, v195, v211
	v_fma_f32 v219, v6, v203, v219
	v_mul_f32_e32 v220, 0xbfb8aa3b, v204
	v_mul_f32_e32 v221, 0xbfb8aa3b, v205
	v_mul_f32_e32 v222, 0xbfb8aa3b, v206
	v_mul_f32_e32 v223, 0xbfb8aa3b, v207
	v_mul_f32_e32 v224, 0xbfb8aa3b, v208
	v_mul_f32_e32 v225, 0xbfb8aa3b, v209
	v_mul_f32_e32 v226, 0xbfb8aa3b, v210
	v_mul_f32_e32 v227, 0xbfb8aa3b, v211
	v_exp_f32_e32 v220, v220
	v_exp_f32_e32 v221, v221
	v_exp_f32_e32 v222, v222
	v_exp_f32_e32 v223, v223
	v_exp_f32_e32 v224, v224
	v_exp_f32_e32 v225, v225
	v_exp_f32_e32 v226, v226
	v_exp_f32_e32 v227, v227
	v_add_f32_e32 v220, 1.0, v220
	v_add_f32_e32 v221, 1.0, v221
	v_add_f32_e32 v222, 1.0, v222
	v_add_f32_e32 v223, 1.0, v223
	v_add_f32_e32 v224, 1.0, v224
	v_add_f32_e32 v225, 1.0, v225
	v_add_f32_e32 v226, 1.0, v226
	v_add_f32_e32 v227, 1.0, v227
	v_rcp_f32_e32 v220, v220
	v_rcp_f32_e32 v221, v221
	v_rcp_f32_e32 v222, v222
	v_rcp_f32_e32 v223, v223
	v_rcp_f32_e32 v224, v224
	v_rcp_f32_e32 v225, v225
	v_rcp_f32_e32 v226, v226
	v_rcp_f32_e32 v227, v227
	v_mov_b32_e32 v15, v194
	v_mov_b32_e32 v10, v195
	v_mov_b32_e32 v14, v202
	v_mov_b32_e32 v11, v203
	v_mul_f32_e32 v204, v204, v220
	v_mul_f32_e32 v205, v205, v221
	v_mul_f32_e32 v206, v206, v222
	v_mul_f32_e32 v207, v207, v223
	v_mul_f32_e32 v208, v208, v224
	v_mul_f32_e32 v209, v209, v225
	v_mul_f32_e32 v210, v210, v226
	v_mul_f32_e32 v211, v211, v227
	v_mul_f32_e32 v212, v212, v204
	v_mul_f32_e32 v213, v213, v205
	v_mul_f32_e32 v214, v214, v206
	v_mul_f32_e32 v215, v215, v207
	v_mul_f32_e32 v216, v216, v208
	v_mul_f32_e32 v217, v217, v209
	v_mul_f32_e32 v218, v218, v210
	v_mul_f32_e32 v219, v219, v211
	v_cvt_pk_bf16_f32 v212, v212, v212
	v_cvt_pk_bf16_f32 v213, v213, v213
	v_cvt_pk_bf16_f32 v214, v214, v214
	v_cvt_pk_bf16_f32 v215, v215, v215
	v_cvt_pk_bf16_f32 v216, v216, v216
	v_cvt_pk_bf16_f32 v217, v217, v217
	v_cvt_pk_bf16_f32 v218, v218, v218
	v_cvt_pk_bf16_f32 v219, v219, v219
	v_cmp_lt_i32_e32 vcc, v32, v40
	s_and_b64 exec, exec, vcc
	global_store_short v24, v212, s[42:43]
	v_cmp_lt_i32_e32 vcc, v33, v40
	s_and_b64 exec, exec, vcc
	global_store_short v25, v213, s[42:43]
	v_cmp_lt_i32_e32 vcc, v34, v40
	s_and_b64 exec, exec, vcc
	global_store_short v26, v214, s[42:43]
	v_cmp_lt_i32_e32 vcc, v35, v40
	s_and_b64 exec, exec, vcc
	global_store_short v27, v215, s[42:43]
	v_cmp_lt_i32_e32 vcc, v36, v40
	s_and_b64 exec, exec, vcc
	global_store_short v28, v216, s[42:43]
	v_cmp_lt_i32_e32 vcc, v37, v40
	s_and_b64 exec, exec, vcc
	global_store_short v29, v217, s[42:43]
	v_cmp_lt_i32_e32 vcc, v38, v40
	s_and_b64 exec, exec, vcc
	global_store_short v30, v218, s[42:43]
	v_cmp_lt_i32_e32 vcc, v39, v40
	s_and_b64 exec, exec, vcc
	global_store_short v31, v219, s[42:43]
	s_mov_b64 exec, -1
	v_add_u32_e32 v17, 0x1020, v17
	v_add_u32_e32 v18, 8, v18
	s_sub_u32 s62, s62, 1
	s_cmp_lg_u32 s62, 0
	s_cbranch_scc1 .Lcv12_loop
	s_branch .LBB0_2363
